# phase_mid and phase_final rewritten by hand: wave-per-row loops with every load of a row issued together one row ahead (counted vmcnt), DPP+2 bpermute reductions; on top of MLA QK prefetch + permuted
# speedup vs baseline: 1.0373x; 1.0373x over previous
; DI int otid() { int t = threadIdx.x; asm volatile("" : "+v"(t)); return t; }
; DI int obid() { int b = blockIdx.x; asm volatile("" : "+s"(b)); return b; }
; DI int ogrid() { int g = gridDim.x; asm volatile("" : "+s"(g)); return g; }
; DI float bf_lo(unsigned u) { return __uint_as_float(u << 16); }
; DI float bf_hi(unsigned u) { return __uint_as_float(u & 0xffff0000u); }
; DI void phase_final(KP P) {
;     const int tid_ = otid(), lane = tid_ & 63, gw = obid() * 8 + (tid_ >> 6), nw = ogrid() * 8;
;     for (int row = gw; row < MT; row += nw) {
;         const float* ad = P->ada + ada_b(row) * 6144;
;         f32x4 fv[4]; float s = 0.f;
; #pragma unroll
;         for (int i = 0; i < 4; ++i) { const u32x2 wv = *(const u32x2*)(P->f + (long)row * DM + i * 256 + lane * 4);
;             fv[i] = (f32x4){bf_lo(wv.x), bf_hi(wv.x), bf_lo(wv.y), bf_hi(wv.y)}; s += fv[i][0] * fv[i][0] + fv[i][1] * fv[i][1] + fv[i][2] * fv[i][2] + fv[i][3] * fv[i][3]; }
; #pragma unroll
;         for (int o = 1; o < 64; o <<= 1) s += __shfl_xor(s, o);
;         const float rstd = rsqrtf(s * (1.0f / DM) + EPS);
; #pragma unroll
;         for (int i = 0; i < 4; ++i) { const int c = i * 256 + lane * 4; float* yp = P->out + O_Y + (long)row * DM + c;
;             const f32x4 xv = *(const f32x4*)yp, g = *(const f32x4*)(P->g_post_ffn + c), gt = *(const f32x4*)(ad + 5120 + c);
;             *(f32x4*)yp = xv + gt * (fv[i] * rstd * g); }
;     }
; }
.LBB0_291:
	s_mov_b64 s[2:3], 0
	v_writelane_b32 v251, s2, 23
	s_mov_b64 s[6:7], -1
	s_mov_b64 s[10:11], 0
	s_cmp_lt_i32 s38, 10
	v_writelane_b32 v251, s3, 24
	s_mov_b64 s[2:3], 0
	s_cbranch_scc1 .LBB0_401
	v_writelane_b32 v251, s2, 23
	s_cmp_gt_i32 s38, 11
	s_nop 0
	v_writelane_b32 v251, s3, 24
	s_mov_b64 s[2:3], 0
	s_cbranch_scc0 .LBB0_301
	s_cmp_eq_u32 s38, 12
	s_mov_b64 s[2:3], -1
	s_cbranch_scc0 .LBB0_300
	v_readlane_b32 s2, v251, 16
	v_readlane_b32 s3, v251, 17
	s_and_b64 vcc, exec, s[2:3]
	s_cbranch_vccnz .LBB0_299
	s_load_dwordx2 s[8:9], s[0:1], 0xe8
	s_load_dwordx2 s[12:13], s[0:1], 0x90
	s_load_dwordx2 s[14:15], s[0:1], 0x198
	s_load_dwordx2 s[16:17], s[0:1], 0x70
	s_waitcnt lgkmcnt(0)
	v_lshrrev_b32_e32 v4, 6, v186
	v_and_b32_e32 v1, 63, v186
	s_lshl_b32 s18, s54, 3
	s_lshl_b32 s19, s55, 3
	v_readfirstlane_b32 s6, v4
	v_lshlrev_b32_e32 v0, 4, v1
	v_lshlrev_b32_e32 v2, 3, v1
	v_xor_b32_e32 v3, 16, v1
	v_lshlrev_b32_e32 v6, 2, v3
	v_xor_b32_e32 v3, 32, v1
	v_lshlrev_b32_e32 v7, 2, v3
	v_add_u32_e32 v3, 0x5000, v0
	s_add_i32 s18, s18, s6
	s_cmpk_ge_i32 s18, 0x4100
	s_cbranch_scc1 .Lpf_done
	s_waitcnt lgkmcnt(0)
	global_load_dwordx4 v[8:11], v0, s[16:17]
	global_load_dwordx4 v[12:15], v0, s[16:17] offset:1024
	global_load_dwordx4 v[16:19], v0, s[16:17] offset:2048
	global_load_dwordx4 v[20:23], v0, s[16:17] offset:3072
	s_add_i32 s24, s18, 0xffffc000
	s_lshr_b32 s22, s18, 13
	s_lshr_b32 s23, s24, 5
	s_add_i32 s23, s23, 2
	s_cmp_lt_i32 s18, 0x4000
	s_cselect_b32 s22, s22, s23
	s_mul_i32 s22, s22, 0x6000
	s_add_u32 s22, s8, s22
	s_addc_u32 s23, s9, 0
	s_lshl_b32 s24, s18, 11
	s_add_u32 s20, s14, s24
	s_addc_u32 s21, s15, 0
	s_lshl_b32 s24, s18, 12
	s_add_u32 s24, s12, s24
	s_addc_u32 s25, s13, 0
	global_load_dwordx2 v[64:65], v2, s[20:21]
	global_load_dwordx2 v[66:67], v2, s[20:21] offset:512
	global_load_dwordx2 v[68:69], v2, s[20:21] offset:1024
	global_load_dwordx2 v[70:71], v2, s[20:21] offset:1536
	global_load_dwordx4 v[72:75], v0, s[24:25]
	global_load_dwordx4 v[76:79], v0, s[24:25] offset:1024
	global_load_dwordx4 v[80:83], v0, s[24:25] offset:2048
	global_load_dwordx4 v[84:87], v0, s[24:25] offset:3072
	global_load_dwordx4 v[88:91], v3, s[22:23]
	global_load_dwordx4 v[92:95], v3, s[22:23] offset:1024
	global_load_dwordx4 v[96:99], v3, s[22:23] offset:2048
	global_load_dwordx4 v[100:103], v3, s[22:23] offset:3072
	s_waitcnt vmcnt(0)
	s_branch .Lpf_body
.Lpf_loop:
	s_waitcnt vmcnt(4)
.Lpf_body:
	v_mov_b64_e32 v[24:25], v[64:65]
	v_mov_b64_e32 v[26:27], v[66:67]
	v_mov_b64_e32 v[28:29], v[68:69]
	v_mov_b64_e32 v[30:31], v[70:71]
	v_mov_b64_e32 v[32:33], v[72:73]
	v_mov_b64_e32 v[34:35], v[74:75]
	v_mov_b64_e32 v[36:37], v[76:77]
	v_mov_b64_e32 v[38:39], v[78:79]
	v_mov_b64_e32 v[40:41], v[80:81]
	v_mov_b64_e32 v[42:43], v[82:83]
	v_mov_b64_e32 v[44:45], v[84:85]
	v_mov_b64_e32 v[46:47], v[86:87]
	v_mov_b64_e32 v[48:49], v[88:89]
	v_mov_b64_e32 v[50:51], v[90:91]
	v_mov_b64_e32 v[52:53], v[92:93]
	v_mov_b64_e32 v[54:55], v[94:95]
	v_mov_b64_e32 v[56:57], v[96:97]
	v_mov_b64_e32 v[58:59], v[98:99]
	v_mov_b64_e32 v[60:61], v[100:101]
	v_mov_b64_e32 v[62:63], v[102:103]
	s_add_i32 s27, s18, s19
	s_cmpk_ge_i32 s27, 0x4100
	s_cbranch_scc1 .Lpf_nonext
	s_add_i32 s24, s27, 0xffffc000
	s_lshr_b32 s22, s27, 13
	s_lshr_b32 s23, s24, 5
	s_add_i32 s23, s23, 2
	s_cmp_lt_i32 s27, 0x4000
	s_cselect_b32 s22, s22, s23
	s_mul_i32 s22, s22, 0x6000
	s_add_u32 s22, s8, s22
	s_addc_u32 s23, s9, 0
	s_lshl_b32 s24, s27, 11
	s_add_u32 s20, s14, s24
	s_addc_u32 s21, s15, 0
	s_lshl_b32 s24, s27, 12
	s_add_u32 s24, s12, s24
	s_addc_u32 s25, s13, 0
	global_load_dwordx2 v[64:65], v2, s[20:21]
	global_load_dwordx2 v[66:67], v2, s[20:21] offset:512
	global_load_dwordx2 v[68:69], v2, s[20:21] offset:1024
	global_load_dwordx2 v[70:71], v2, s[20:21] offset:1536
	global_load_dwordx4 v[72:75], v0, s[24:25]
	global_load_dwordx4 v[76:79], v0, s[24:25] offset:1024
	global_load_dwordx4 v[80:83], v0, s[24:25] offset:2048
	global_load_dwordx4 v[84:87], v0, s[24:25] offset:3072
	global_load_dwordx4 v[88:91], v3, s[22:23]
	global_load_dwordx4 v[92:95], v3, s[22:23] offset:1024
	global_load_dwordx4 v[96:99], v3, s[22:23] offset:2048
	global_load_dwordx4 v[100:103], v3, s[22:23] offset:3072
; DI float bf_lo(unsigned u) { return __uint_as_float(u << 16); }
; DI float bf_hi(unsigned u) { return __uint_as_float(u & 0xffff0000u); }
; DI void phase_final(KP P) {
;     ...
;         for (int i = 0; i < 4; ++i) { const u32x2 wv = *(const u32x2*)(P->f + (long)row * DM + i * 256 + lane * 4);
;             fv[i] = (f32x4){bf_lo(wv.x), bf_hi(wv.x), bf_lo(wv.y), bf_hi(wv.y)}; s += fv[i][0] * fv[i][0] + fv[i][1] * fv[i][1] + fv[i][2] * fv[i][2] + fv[i][3] * fv[i][3]; }
; #pragma unroll
;         for (int o = 1; o < 64; o <<= 1) s += __shfl_xor(s, o);
;         const float rstd = rsqrtf(s * (1.0f / DM) + EPS);
; #pragma unroll
;         for (int i = 0; i < 4; ++i) { const int c = i * 256 + lane * 4; float* yp = P->out + O_Y + (long)row * DM + c;
;             const f32x4 xv = *(const f32x4*)yp, g = *(const f32x4*)(P->g_post_ffn + c), gt = *(const f32x4*)(ad + 5120 + c);
;             *(f32x4*)yp = xv + gt * (fv[i] * rstd * g); }
.Lpf_nonext:
	v_lshlrev_b32_e32 v104, 16, v24
	v_and_b32_e32 v105, 0xffff0000, v24
	v_lshlrev_b32_e32 v106, 16, v25
	v_and_b32_e32 v107, 0xffff0000, v25
	v_lshlrev_b32_e32 v108, 16, v26
	v_and_b32_e32 v109, 0xffff0000, v26
	v_lshlrev_b32_e32 v110, 16, v27
	v_and_b32_e32 v111, 0xffff0000, v27
	v_lshlrev_b32_e32 v112, 16, v28
	v_and_b32_e32 v113, 0xffff0000, v28
	v_lshlrev_b32_e32 v114, 16, v29
	v_and_b32_e32 v115, 0xffff0000, v29
	v_lshlrev_b32_e32 v116, 16, v30
	v_and_b32_e32 v117, 0xffff0000, v30
	v_lshlrev_b32_e32 v118, 16, v31
	v_and_b32_e32 v119, 0xffff0000, v31
	v_mul_f32_e32 v120, v104, v104
	v_mul_f32_e32 v121, v105, v105
	v_fmac_f32_e32 v120, v106, v106
	v_fmac_f32_e32 v121, v107, v107
	v_fmac_f32_e32 v120, v108, v108
	v_fmac_f32_e32 v121, v109, v109
	v_fmac_f32_e32 v120, v110, v110
	v_fmac_f32_e32 v121, v111, v111
	v_fmac_f32_e32 v120, v112, v112
	v_fmac_f32_e32 v121, v113, v113
	v_fmac_f32_e32 v120, v114, v114
	v_fmac_f32_e32 v121, v115, v115
	v_fmac_f32_e32 v120, v116, v116
	v_fmac_f32_e32 v121, v117, v117
	v_fmac_f32_e32 v120, v118, v118
	v_fmac_f32_e32 v121, v119, v119
	v_add_f32_e32 v120, v120, v121
	s_nop 1
	v_mov_b32_dpp v121, v120 quad_perm:[1,0,3,2] row_mask:0xf bank_mask:0xf bound_ctrl:1
	v_add_f32_e32 v120, v120, v121
	s_nop 1
	v_mov_b32_dpp v121, v120 quad_perm:[2,3,0,1] row_mask:0xf bank_mask:0xf bound_ctrl:1
	v_add_f32_e32 v120, v120, v121
	s_nop 1
	v_mov_b32_dpp v121, v120 row_ror:4 row_mask:0xf bank_mask:0xf bound_ctrl:1
	v_add_f32_e32 v120, v120, v121
	s_nop 1
	v_mov_b32_dpp v121, v120 row_ror:8 row_mask:0xf bank_mask:0xf bound_ctrl:1
	v_add_f32_e32 v120, v120, v121
	ds_bpermute_b32 v121, v6, v120
	s_waitcnt lgkmcnt(0)
	v_add_f32_e32 v120, v120, v121
	ds_bpermute_b32 v121, v7, v120
	s_waitcnt lgkmcnt(0)
	v_add_f32_e32 v120, v120, v121
	v_mov_b32_e32 v122, 0x358637bd
	v_fmamk_f32 v120, v120, 0x3a800000, v122
	v_rsq_f32_e32 v120, v120
	s_lshl_b32 s24, s18, 12
	s_add_u32 s20, s12, s24
	s_addc_u32 s21, s13, 0
	v_pk_mul_f32 v[104:105], v[104:105], v[120:121] op_sel_hi:[1,0]
	v_pk_mul_f32 v[106:107], v[106:107], v[120:121] op_sel_hi:[1,0]
	v_pk_mul_f32 v[104:105], v[104:105], v[8:9]
	v_pk_mul_f32 v[106:107], v[106:107], v[10:11]
	v_pk_fma_f32 v[104:105], v[48:49], v[104:105], v[32:33]
	v_pk_fma_f32 v[106:107], v[50:51], v[106:107], v[34:35]
	global_store_dwordx4 v0, v[104:107], s[20:21]
	v_pk_mul_f32 v[108:109], v[108:109], v[120:121] op_sel_hi:[1,0]
	v_pk_mul_f32 v[110:111], v[110:111], v[120:121] op_sel_hi:[1,0]
	v_pk_mul_f32 v[108:109], v[108:109], v[12:13]
	v_pk_mul_f32 v[110:111], v[110:111], v[14:15]
	v_pk_fma_f32 v[108:109], v[52:53], v[108:109], v[36:37]
	v_pk_fma_f32 v[110:111], v[54:55], v[110:111], v[38:39]
	global_store_dwordx4 v0, v[108:111], s[20:21] offset:1024
	v_pk_mul_f32 v[112:113], v[112:113], v[120:121] op_sel_hi:[1,0]
	v_pk_mul_f32 v[114:115], v[114:115], v[120:121] op_sel_hi:[1,0]
	v_pk_mul_f32 v[112:113], v[112:113], v[16:17]
	v_pk_mul_f32 v[114:115], v[114:115], v[18:19]
	v_pk_fma_f32 v[112:113], v[56:57], v[112:113], v[40:41]
	v_pk_fma_f32 v[114:115], v[58:59], v[114:115], v[42:43]
	global_store_dwordx4 v0, v[112:115], s[20:21] offset:2048
	v_pk_mul_f32 v[116:117], v[116:117], v[120:121] op_sel_hi:[1,0]
	v_pk_mul_f32 v[118:119], v[118:119], v[120:121] op_sel_hi:[1,0]
	v_pk_mul_f32 v[116:117], v[116:117], v[20:21]
	v_pk_mul_f32 v[118:119], v[118:119], v[22:23]
	v_pk_fma_f32 v[116:117], v[60:61], v[116:117], v[44:45]
	v_pk_fma_f32 v[118:119], v[62:63], v[118:119], v[46:47]
	global_store_dwordx4 v0, v[116:119], s[20:21] offset:3072
	s_mov_b32 s18, s27
	s_cmpk_lt_i32 s18, 0x4100
	s_cbranch_scc1 .Lpf_loop
.Lpf_done:
	s_mov_b64 s[2:3], exec
.LBB0_298:
	s_or_b64 exec, exec, s[2:3]

; DI float bf_lo(unsigned u) { return __uint_as_float(u << 16); }
; DI float bf_hi(unsigned u) { return __uint_as_float(u & 0xffff0000u); }
; DI void phase_mid(KP P) {
;     ...
;     for (int row = gw; row < MT; row += nw) {
;         const float* xr = row < MP ? P->x_p + (long)row * DM : P->x_s + (long)(row - MP) * DM;
;         const float* ad = P->ada + ada_b(row) * 6144;
;         f32x4 mv[4]; float s = 0.f;
; #pragma unroll
;         for (int i = 0; i < 4; ++i) { const u32x2 wv = *(const u32x2*)(P->m2 + (long)row * DM + i * 256 + lane * 4);
;             mv[i] = (f32x4){bf_lo(wv.x), bf_hi(wv.x), bf_lo(wv.y), bf_hi(wv.y)}; s += mv[i][0] * mv[i][0] + mv[i][1] * mv[i][1] + mv[i][2] * mv[i][2] + mv[i][3] * mv[i][3]; }
; #pragma unroll
;         for (int o = 1; o < 64; o <<= 1) s += __shfl_xor(s, o);
;         const float rstd = rsqrtf(s * (1.0f / DM) + EPS);
;         float s2 = 0.f;
; #pragma unroll
;         for (int i = 0; i < 4; ++i) { const int c = i * 256 + lane * 4;
;             const f32x4 xv = *(const f32x4*)(xr + c), g = *(const f32x4*)(P->g_post_mix + c), gt = *(const f32x4*)(ad + 2048 + c);
;             mv[i] = xv + gt * (mv[i] * rstd * g);
.LBB0_401:
	s_and_b64 vcc, exec, s[6:7]
	s_cbranch_vccz .LBB0_471
	s_cmp_gt_i32 s38, 7
	s_mov_b64 s[6:7], -1
	s_cbranch_scc0 .LBB0_469
	s_cmp_eq_u32 s38, 8
	s_mov_b64 s[2:3], -1
	s_cbranch_scc0 .LBB0_468
	v_readlane_b32 s2, v251, 8
	v_readlane_b32 s3, v251, 9
	s_andn2_b64 vcc, exec, s[2:3]
	s_cbranch_vccnz .LBB0_413
	s_load_dwordx4 s[8:11], s[0:1], 0x0
	s_load_dwordx4 s[20:23], s[0:1], 0x60
	s_load_dwordx4 s[24:27], s[0:1], 0x178
	s_load_dwordx2 s[14:15], s[0:1], 0xe8
	s_load_dwordx2 s[16:17], s[0:1], 0x90
	s_waitcnt lgkmcnt(0)
	v_lshrrev_b32_e32 v4, 6, v186
	v_and_b32_e32 v1, 63, v186
	s_lshl_b32 s18, s54, 3
	s_lshl_b32 s19, s55, 3
	v_readfirstlane_b32 s6, v4
	v_lshlrev_b32_e32 v0, 4, v1
	v_lshlrev_b32_e32 v2, 3, v1
	v_xor_b32_e32 v3, 16, v1
	v_lshlrev_b32_e32 v6, 2, v3
	v_xor_b32_e32 v3, 32, v1
	v_lshlrev_b32_e32 v7, 2, v3
	v_add_u32_e32 v3, 0x2000, v0
	v_add_u32_e32 v4, 0x3000, v0
	v_add_u32_e32 v5, 0x4000, v0
	s_add_i32 s18, s18, s6
	s_cmpk_ge_i32 s18, 0x4100
	s_cbranch_scc1 .Lpm_done
	s_waitcnt lgkmcnt(0)
	s_mov_b64 s[2:3], s[24:25]
	s_mov_b64 s[6:7], s[26:27]
	global_load_dwordx4 v[8:11], v0, s[20:21]
	global_load_dwordx4 v[12:15], v0, s[20:21] offset:1024
	global_load_dwordx4 v[16:19], v0, s[20:21] offset:2048
	global_load_dwordx4 v[20:23], v0, s[20:21] offset:3072
	global_load_dwordx4 v[24:27], v0, s[22:23]
	global_load_dwordx4 v[28:31], v0, s[22:23] offset:1024
	global_load_dwordx4 v[32:35], v0, s[22:23] offset:2048
	global_load_dwordx4 v[36:39], v0, s[22:23] offset:3072
	s_add_i32 s24, s18, 0xffffc000
	s_lshr_b32 s22, s18, 13
	s_lshr_b32 s23, s24, 5
	s_add_i32 s23, s23, 2
	s_cmp_lt_i32 s18, 0x4000
	s_cselect_b32 s20, s8, s10
	s_cselect_b32 s21, s9, s11
	s_cselect_b32 s24, s18, s24
	s_cselect_b32 s22, s22, s23
	s_lshl_b32 s24, s24, 12
	s_add_u32 s20, s20, s24
	s_addc_u32 s21, s21, 0
	s_mul_i32 s22, s22, 0x6000
	s_add_u32 s22, s14, s22
	s_addc_u32 s23, s15, 0
	s_lshl_b32 s24, s18, 11
	s_add_u32 s24, s2, s24
	s_addc_u32 s25, s3, 0
	global_load_dwordx2 v[112:113], v2, s[24:25]
	global_load_dwordx2 v[114:115], v2, s[24:25] offset:512
	global_load_dwordx2 v[116:117], v2, s[24:25] offset:1024
	global_load_dwordx2 v[118:119], v2, s[24:25] offset:1536
	global_load_dwordx4 v[120:123], v0, s[20:21]
	global_load_dwordx4 v[124:127], v0, s[20:21] offset:1024
	global_load_dwordx4 v[128:131], v0, s[20:21] offset:2048
	global_load_dwordx4 v[132:135], v0, s[20:21] offset:3072
	global_load_dwordx4 v[142:145], v3, s[22:23]
	global_load_dwordx4 v[146:149], v3, s[22:23] offset:1024
	global_load_dwordx4 v[150:153], v3, s[22:23] offset:2048
	global_load_dwordx4 v[154:157], v3, s[22:23] offset:3072
	global_load_dwordx4 v[158:161], v4, s[22:23]
	global_load_dwordx4 v[162:165], v4, s[22:23] offset:1024
	global_load_dwordx4 v[166:169], v4, s[22:23] offset:2048
	global_load_dwordx4 v[170:173], v4, s[22:23] offset:3072
	global_load_dwordx4 v[202:205], v5, s[22:23]
	global_load_dwordx4 v[206:209], v5, s[22:23] offset:1024
	global_load_dwordx4 v[210:213], v5, s[22:23] offset:2048
	global_load_dwordx4 v[214:217], v5, s[22:23] offset:3072
	s_waitcnt vmcnt(0)
	s_branch .Lpm_body
.Lpm_loop:
	s_waitcnt vmcnt(8)
.Lpm_body:
	v_mov_b64_e32 v[40:41], v[112:113]
	v_mov_b64_e32 v[42:43], v[114:115]
	v_mov_b64_e32 v[44:45], v[116:117]
	v_mov_b64_e32 v[46:47], v[118:119]
	v_mov_b64_e32 v[48:49], v[120:121]
	v_mov_b64_e32 v[50:51], v[122:123]
	v_mov_b64_e32 v[52:53], v[124:125]
	v_mov_b64_e32 v[54:55], v[126:127]
	v_mov_b64_e32 v[56:57], v[128:129]
	v_mov_b64_e32 v[58:59], v[130:131]
	v_mov_b64_e32 v[60:61], v[132:133]
	v_mov_b64_e32 v[62:63], v[134:135]
	v_mov_b64_e32 v[64:65], v[142:143]
	v_mov_b64_e32 v[66:67], v[144:145]
	v_mov_b64_e32 v[68:69], v[146:147]
	v_mov_b64_e32 v[70:71], v[148:149]
	v_mov_b64_e32 v[72:73], v[150:151]
	v_mov_b64_e32 v[74:75], v[152:153]
	v_mov_b64_e32 v[76:77], v[154:155]
	v_mov_b64_e32 v[78:79], v[156:157]
	v_mov_b64_e32 v[80:81], v[158:159]
	v_mov_b64_e32 v[82:83], v[160:161]
	v_mov_b64_e32 v[84:85], v[162:163]
	v_mov_b64_e32 v[86:87], v[164:165]
	v_mov_b64_e32 v[88:89], v[166:167]
	v_mov_b64_e32 v[90:91], v[168:169]
	v_mov_b64_e32 v[92:93], v[170:171]
	v_mov_b64_e32 v[94:95], v[172:173]
	v_mov_b64_e32 v[96:97], v[202:203]
	v_mov_b64_e32 v[98:99], v[204:205]
	v_mov_b64_e32 v[100:101], v[206:207]
	v_mov_b64_e32 v[102:103], v[208:209]
	v_mov_b64_e32 v[104:105], v[210:211]
	v_mov_b64_e32 v[106:107], v[212:213]
	v_mov_b64_e32 v[108:109], v[214:215]
	v_mov_b64_e32 v[110:111], v[216:217]
	s_add_i32 s27, s18, s19
	s_cmpk_ge_i32 s27, 0x4100
	s_cbranch_scc1 .Lpm_nonext
	s_add_i32 s24, s27, 0xffffc000
	s_lshr_b32 s22, s27, 13
	s_lshr_b32 s23, s24, 5
	s_add_i32 s23, s23, 2
	s_cmp_lt_i32 s27, 0x4000
	s_cselect_b32 s20, s8, s10
	s_cselect_b32 s21, s9, s11
	s_cselect_b32 s24, s27, s24
	s_cselect_b32 s22, s22, s23
	s_lshl_b32 s24, s24, 12
	s_add_u32 s20, s20, s24
	s_addc_u32 s21, s21, 0
	s_mul_i32 s22, s22, 0x6000
	s_add_u32 s22, s14, s22
	s_addc_u32 s23, s15, 0
	s_lshl_b32 s24, s27, 11
	s_add_u32 s24, s2, s24
	s_addc_u32 s25, s3, 0
	global_load_dwordx2 v[112:113], v2, s[24:25]
	global_load_dwordx2 v[114:115], v2, s[24:25] offset:512
	global_load_dwordx2 v[116:117], v2, s[24:25] offset:1024
	global_load_dwordx2 v[118:119], v2, s[24:25] offset:1536
	global_load_dwordx4 v[120:123], v0, s[20:21]
	global_load_dwordx4 v[124:127], v0, s[20:21] offset:1024
	global_load_dwordx4 v[128:131], v0, s[20:21] offset:2048
	global_load_dwordx4 v[132:135], v0, s[20:21] offset:3072
	global_load_dwordx4 v[142:145], v3, s[22:23]
	global_load_dwordx4 v[146:149], v3, s[22:23] offset:1024
	global_load_dwordx4 v[150:153], v3, s[22:23] offset:2048
	global_load_dwordx4 v[154:157], v3, s[22:23] offset:3072
	global_load_dwordx4 v[158:161], v4, s[22:23]
	global_load_dwordx4 v[162:165], v4, s[22:23] offset:1024
	global_load_dwordx4 v[166:169], v4, s[22:23] offset:2048
	global_load_dwordx4 v[170:173], v4, s[22:23] offset:3072
	global_load_dwordx4 v[202:205], v5, s[22:23]
	global_load_dwordx4 v[206:209], v5, s[22:23] offset:1024
	global_load_dwordx4 v[210:213], v5, s[22:23] offset:2048
	global_load_dwordx4 v[214:217], v5, s[22:23] offset:3072
; DI float bf_lo(unsigned u) { return __uint_as_float(u << 16); }
; DI float bf_hi(unsigned u) { return __uint_as_float(u & 0xffff0000u); }
; DI void phase_mid(KP P) {
;     ...
;         for (int i = 0; i < 4; ++i) { const u32x2 wv = *(const u32x2*)(P->m2 + (long)row * DM + i * 256 + lane * 4);
;             mv[i] = (f32x4){bf_lo(wv.x), bf_hi(wv.x), bf_lo(wv.y), bf_hi(wv.y)}; s += mv[i][0] * mv[i][0] + mv[i][1] * mv[i][1] + mv[i][2] * mv[i][2] + mv[i][3] * mv[i][3]; }
; #pragma unroll
;         for (int o = 1; o < 64; o <<= 1) s += __shfl_xor(s, o);
;         const float rstd = rsqrtf(s * (1.0f / DM) + EPS);
;         float s2 = 0.f;
; #pragma unroll
;         for (int i = 0; i < 4; ++i) { const int c = i * 256 + lane * 4;
;             const f32x4 xv = *(const f32x4*)(xr + c), g = *(const f32x4*)(P->g_post_mix + c), gt = *(const f32x4*)(ad + 2048 + c);
;             mv[i] = xv + gt * (mv[i] * rstd * g);
;             *(f32x4*)(P->out + O_Y + (long)row * DM + c) = mv[i];
;             s2 += mv[i][0] * mv[i][0] + mv[i][1] * mv[i][1] + mv[i][2] * mv[i][2] + mv[i][3] * mv[i][3]; }
; #pragma unroll
;         for (int o = 1; o < 64; o <<= 1) s2 += __shfl_xor(s2, o);
;         const float rstd2 = rsqrtf(s2 * (1.0f / DM) + EPS);
.Lpm_nonext:
	v_lshlrev_b32_e32 v218, 16, v40
	v_and_b32_e32 v219, 0xffff0000, v40
	v_lshlrev_b32_e32 v220, 16, v41
	v_and_b32_e32 v221, 0xffff0000, v41
	v_lshlrev_b32_e32 v222, 16, v42
	v_and_b32_e32 v223, 0xffff0000, v42
	v_lshlrev_b32_e32 v224, 16, v43
	v_and_b32_e32 v225, 0xffff0000, v43
	v_lshlrev_b32_e32 v226, 16, v44
	v_and_b32_e32 v227, 0xffff0000, v44
	v_lshlrev_b32_e32 v228, 16, v45
	v_and_b32_e32 v229, 0xffff0000, v45
	v_lshlrev_b32_e32 v230, 16, v46
	v_and_b32_e32 v231, 0xffff0000, v46
	v_lshlrev_b32_e32 v232, 16, v47
	v_and_b32_e32 v233, 0xffff0000, v47
	v_mul_f32_e32 v234, v218, v218
	v_mul_f32_e32 v235, v219, v219
	v_fmac_f32_e32 v234, v220, v220
	v_fmac_f32_e32 v235, v221, v221
	v_fmac_f32_e32 v234, v222, v222
	v_fmac_f32_e32 v235, v223, v223
	v_fmac_f32_e32 v234, v224, v224
	v_fmac_f32_e32 v235, v225, v225
	v_fmac_f32_e32 v234, v226, v226
	v_fmac_f32_e32 v235, v227, v227
	v_fmac_f32_e32 v234, v228, v228
	v_fmac_f32_e32 v235, v229, v229
	v_fmac_f32_e32 v234, v230, v230
	v_fmac_f32_e32 v235, v231, v231
	v_fmac_f32_e32 v234, v232, v232
	v_fmac_f32_e32 v235, v233, v233
	v_add_f32_e32 v234, v234, v235
	s_nop 1
	v_mov_b32_dpp v235, v234 quad_perm:[1,0,3,2] row_mask:0xf bank_mask:0xf bound_ctrl:1
	v_add_f32_e32 v234, v234, v235
	s_nop 1
	v_mov_b32_dpp v235, v234 quad_perm:[2,3,0,1] row_mask:0xf bank_mask:0xf bound_ctrl:1
	v_add_f32_e32 v234, v234, v235
	s_nop 1
	v_mov_b32_dpp v235, v234 row_ror:4 row_mask:0xf bank_mask:0xf bound_ctrl:1
	v_add_f32_e32 v234, v234, v235
	s_nop 1
	v_mov_b32_dpp v235, v234 row_ror:8 row_mask:0xf bank_mask:0xf bound_ctrl:1
	v_add_f32_e32 v234, v234, v235
	ds_bpermute_b32 v235, v6, v234
	s_waitcnt lgkmcnt(0)
	v_add_f32_e32 v234, v234, v235
	ds_bpermute_b32 v235, v7, v234
	s_waitcnt lgkmcnt(0)
	v_add_f32_e32 v234, v234, v235
	v_mov_b32_e32 v236, 0x358637bd
	v_fmamk_f32 v234, v234, 0x3a800000, v236
	v_rsq_f32_e32 v234, v234
	s_lshl_b32 s24, s18, 12
	s_add_u32 s20, s16, s24
	s_addc_u32 s21, s17, 0
	s_lshl_b32 s24, s18, 11
	s_add_u32 s22, s6, s24
	s_addc_u32 s23, s7, 0
	v_pk_mul_f32 v[218:219], v[218:219], v[234:235] op_sel_hi:[1,0]
	v_pk_mul_f32 v[220:221], v[220:221], v[234:235] op_sel_hi:[1,0]
	v_pk_mul_f32 v[218:219], v[218:219], v[8:9]
	v_pk_mul_f32 v[220:221], v[220:221], v[10:11]
	v_pk_fma_f32 v[218:219], v[64:65], v[218:219], v[48:49]
	v_pk_fma_f32 v[220:221], v[66:67], v[220:221], v[50:51]
	global_store_dwordx4 v0, v[218:221], s[20:21]
	v_pk_mul_f32 v[222:223], v[222:223], v[234:235] op_sel_hi:[1,0]
	v_pk_mul_f32 v[224:225], v[224:225], v[234:235] op_sel_hi:[1,0]
	v_pk_mul_f32 v[222:223], v[222:223], v[12:13]
	v_pk_mul_f32 v[224:225], v[224:225], v[14:15]
	v_pk_fma_f32 v[222:223], v[68:69], v[222:223], v[52:53]
	v_pk_fma_f32 v[224:225], v[70:71], v[224:225], v[54:55]
	global_store_dwordx4 v0, v[222:225], s[20:21] offset:1024
	v_pk_mul_f32 v[226:227], v[226:227], v[234:235] op_sel_hi:[1,0]
	v_pk_mul_f32 v[228:229], v[228:229], v[234:235] op_sel_hi:[1,0]
	v_pk_mul_f32 v[226:227], v[226:227], v[16:17]
	v_pk_mul_f32 v[228:229], v[228:229], v[18:19]
	v_pk_fma_f32 v[226:227], v[72:73], v[226:227], v[56:57]
	v_pk_fma_f32 v[228:229], v[74:75], v[228:229], v[58:59]
	global_store_dwordx4 v0, v[226:229], s[20:21] offset:2048
	v_pk_mul_f32 v[230:231], v[230:231], v[234:235] op_sel_hi:[1,0]
	v_pk_mul_f32 v[232:233], v[232:233], v[234:235] op_sel_hi:[1,0]
	v_pk_mul_f32 v[230:231], v[230:231], v[20:21]
	v_pk_mul_f32 v[232:233], v[232:233], v[22:23]
	v_pk_fma_f32 v[230:231], v[76:77], v[230:231], v[60:61]
	v_pk_fma_f32 v[232:233], v[78:79], v[232:233], v[62:63]
	global_store_dwordx4 v0, v[230:233], s[20:21] offset:3072
	v_mul_f32_e32 v238, v218, v218
	v_mul_f32_e32 v239, v219, v219
	v_fmac_f32_e32 v238, v220, v220
	v_fmac_f32_e32 v239, v221, v221
	v_fmac_f32_e32 v238, v222, v222
	v_fmac_f32_e32 v239, v223, v223
	v_fmac_f32_e32 v238, v224, v224
	v_fmac_f32_e32 v239, v225, v225
	v_fmac_f32_e32 v238, v226, v226
	v_fmac_f32_e32 v239, v227, v227
	v_fmac_f32_e32 v238, v228, v228
	v_fmac_f32_e32 v239, v229, v229
	v_fmac_f32_e32 v238, v230, v230
	v_fmac_f32_e32 v239, v231, v231
	v_fmac_f32_e32 v238, v232, v232
	v_fmac_f32_e32 v239, v233, v233
	v_add_f32_e32 v238, v238, v239
	s_nop 1
	v_mov_b32_dpp v239, v238 quad_perm:[1,0,3,2] row_mask:0xf bank_mask:0xf bound_ctrl:1
	v_add_f32_e32 v238, v238, v239
	s_nop 1
	v_mov_b32_dpp v239, v238 quad_perm:[2,3,0,1] row_mask:0xf bank_mask:0xf bound_ctrl:1
	v_add_f32_e32 v238, v238, v239
	s_nop 1
	v_mov_b32_dpp v239, v238 row_ror:4 row_mask:0xf bank_mask:0xf bound_ctrl:1
	v_add_f32_e32 v238, v238, v239
	s_nop 1
	v_mov_b32_dpp v239, v238 row_ror:8 row_mask:0xf bank_mask:0xf bound_ctrl:1
	v_add_f32_e32 v238, v238, v239
	ds_bpermute_b32 v239, v6, v238
	s_waitcnt lgkmcnt(0)
; DI void store_bf4(bf16_t* p, f32x4 v) { u32x2 w; w.x = pk2(v[0], v[1]); w.y = pk2(v[2], v[3]); *(u32x2*)p = w; }
; DI void phase_mid(KP P) {
;     ...
;         for (int o = 1; o < 64; o <<= 1) s2 += __shfl_xor(s2, o);
;         const float rstd2 = rsqrtf(s2 * (1.0f / DM) + EPS);
; #pragma unroll
;         for (int i = 0; i < 4; ++i) { const int c = i * 256 + lane * 4;
;             const f32x4 g = *(const f32x4*)(P->g_pre_ffn + c), sh = *(const f32x4*)(ad + 3072 + c), scl = *(const f32x4*)(ad + 4096 + c);
;             store_bf4(P->h2 + (long)row * DM + c, mv[i] * rstd2 * g * (1.0f + scl) + sh); }
	v_add_f32_e32 v238, v238, v239
	ds_bpermute_b32 v239, v7, v238
	s_waitcnt lgkmcnt(0)
	v_add_f32_e32 v238, v238, v239
	v_mov_b32_e32 v236, 0x358637bd
	v_fmamk_f32 v238, v238, 0x3a800000, v236
	v_rsq_f32_e32 v238, v238
	s_nop 0
	v_pk_mul_f32 v[240:241], v[218:219], v[238:239] op_sel_hi:[1,0]
	v_pk_mul_f32 v[242:243], v[220:221], v[238:239] op_sel_hi:[1,0]
	v_pk_add_f32 v[244:245], v[96:97], 1.0 op_sel_hi:[1,0]
	v_pk_add_f32 v[246:247], v[98:99], 1.0 op_sel_hi:[1,0]
	v_pk_mul_f32 v[240:241], v[24:25], v[240:241]
	v_pk_mul_f32 v[242:243], v[26:27], v[242:243]
	v_pk_fma_f32 v[240:241], v[244:245], v[240:241], v[80:81]
	v_pk_fma_f32 v[242:243], v[246:247], v[242:243], v[82:83]
	v_cvt_pk_bf16_f32 v218, v240, v241
	v_cvt_pk_bf16_f32 v219, v242, v243
	global_store_dwordx2 v2, v[218:219], s[22:23]
	v_pk_mul_f32 v[240:241], v[222:223], v[238:239] op_sel_hi:[1,0]
	v_pk_mul_f32 v[242:243], v[224:225], v[238:239] op_sel_hi:[1,0]
	v_pk_add_f32 v[244:245], v[100:101], 1.0 op_sel_hi:[1,0]
	v_pk_add_f32 v[246:247], v[102:103], 1.0 op_sel_hi:[1,0]
	v_pk_mul_f32 v[240:241], v[28:29], v[240:241]
	v_pk_mul_f32 v[242:243], v[30:31], v[242:243]
	v_pk_fma_f32 v[240:241], v[244:245], v[240:241], v[84:85]
	v_pk_fma_f32 v[242:243], v[246:247], v[242:243], v[86:87]
	v_cvt_pk_bf16_f32 v222, v240, v241
	v_cvt_pk_bf16_f32 v223, v242, v243
	global_store_dwordx2 v2, v[222:223], s[22:23] offset:512
	v_pk_mul_f32 v[240:241], v[226:227], v[238:239] op_sel_hi:[1,0]
	v_pk_mul_f32 v[242:243], v[228:229], v[238:239] op_sel_hi:[1,0]
	v_pk_add_f32 v[244:245], v[104:105], 1.0 op_sel_hi:[1,0]
	v_pk_add_f32 v[246:247], v[106:107], 1.0 op_sel_hi:[1,0]
	v_pk_mul_f32 v[240:241], v[32:33], v[240:241]
	v_pk_mul_f32 v[242:243], v[34:35], v[242:243]
	v_pk_fma_f32 v[240:241], v[244:245], v[240:241], v[88:89]
	v_pk_fma_f32 v[242:243], v[246:247], v[242:243], v[90:91]
	v_cvt_pk_bf16_f32 v226, v240, v241
	v_cvt_pk_bf16_f32 v227, v242, v243
	global_store_dwordx2 v2, v[226:227], s[22:23] offset:1024
	v_pk_mul_f32 v[240:241], v[230:231], v[238:239] op_sel_hi:[1,0]
	v_pk_mul_f32 v[242:243], v[232:233], v[238:239] op_sel_hi:[1,0]
	v_pk_add_f32 v[244:245], v[108:109], 1.0 op_sel_hi:[1,0]
	v_pk_add_f32 v[246:247], v[110:111], 1.0 op_sel_hi:[1,0]
	v_pk_mul_f32 v[240:241], v[36:37], v[240:241]
	v_pk_mul_f32 v[242:243], v[38:39], v[242:243]
	v_pk_fma_f32 v[240:241], v[244:245], v[240:241], v[92:93]
	v_pk_fma_f32 v[242:243], v[246:247], v[242:243], v[94:95]
	v_cvt_pk_bf16_f32 v230, v240, v241
	v_cvt_pk_bf16_f32 v231, v242, v243
	global_store_dwordx2 v2, v[230:231], s[22:23] offset:1536
	s_mov_b32 s18, s27
	s_cmpk_lt_i32 s18, 0x4100
	s_cbranch_scc1 .Lpm_loop
.Lpm_done:
	s_mov_b64 s[12:13], exec
